# P0: the 256 waves computing the S5 constants (two items each) skip the third weight-conversion pass, which is spread over the other 1792 waves
# baseline (speedup 1.0000x reference)
.LBB0_49:
	s_lshl_b32 s3, s3, 3
	s_add_i32 s3, s3, s34
	s_cmpk_gt_i32 s3, 0x16ff
	s_waitcnt lgkmcnt(0)
	s_barrier
	s_cbranch_scc1 .LBB0_92
	s_lshl_b32 s35, s30, 3
	s_add_u32 s4, s70, 0x1300000
	s_addc_u32 s5, s71, 0
	s_add_u32 s6, s70, 0x800000
	s_addc_u32 s7, s71, 0
	s_add_u32 s8, s70, 0x600000
	v_lshlrev_b32_e32 v0, 4, v196
	s_addc_u32 s9, s71, 0
	v_and_b32_e32 v0, 0xf0, v0
	v_mov_b32_e32 v1, 0
	v_lshl_add_u64 v[2:3], s[70:71], 0, v[0:1]
	s_mov_b64 s[0:1], 0x500000
	s_add_u32 s52, s70, 0x100000
	v_or_b32_e32 v78, 0xfffff700, v139
	v_or_b32_e32 v79, 0xfffff000, v139
	v_lshl_add_u64 v[2:3], v[2:3], 0, s[0:1]
	v_and_b32_e32 v80, 31, v196
	s_addc_u32 s53, s71, 0
	s_movk_i32 s89, 0xf00
	s_lshl_b32 s90, s3, 5
	s_mov_b32 s91, 0x1e000
	s_lshl_b32 s92, s3, 1
	s_movk_i32 s93, 0x1e00
	s_lshl_b32 s94, s3, 2
	s_movk_i32 s95, 0x3c00
	s_mov_b32 s59, 0
	s_movk_i32 s33, 0x1600
	s_movk_i32 s97, 0x80
	s_movk_i32 s87, 0x5ff
	s_movk_i32 s86, 0x7fff
	s_mov_b32 s10, 0xffff0000
	v_mov_b32_e32 v81, 0xff
	s_mov_b32 s11, s3
	s_branch .LBB0_52
.LBB0_51:
	s_cmpk_lt_i32 s3, 0x100
	s_cbranch_scc1 .LBB0_92
	s_add_i32 s11, s11, s89
	s_add_i32 s90, s90, s91
	s_add_i32 s92, s92, s93
	s_add_i32 s94, s94, s95
	s_cmpk_gt_i32 s11, 0x16ff
	s_cbranch_scc1 .LBB0_92

.LBB0_92:
	v_lshl_or_b32 v0, s3, 6, v139
	s_movk_i32 s0, 0x4000
	v_cmp_gt_i32_e32 vcc, s0, v0
	s_and_saveexec_b64 s[12:13], vcc
	v_readlane_b32 s92, v255, 3
	v_readlane_b32 s93, v255, 4
	v_readlane_b32 s94, v255, 2
	v_readlane_b32 s95, v255, 1
	v_readlane_b32 s33, v255, 0
	s_cbranch_execz .LBB0_105
	s_add_u32 s14, s70, 0x1a00000
	s_addc_u32 s15, s71, 0
	s_add_u32 s16, s70, 0x1a80000
	s_addc_u32 s17, s71, 0
	s_add_u32 s18, s70, 0x1ac0000
	s_addc_u32 s19, s71, 0
	s_movk_i32 s20, 0x4000
	v_ashrrev_i32_e32 v1, 31, v0
	s_ashr_i32 s21, s20, 31
	v_cmp_eq_u32_e64 s[0:1], 0, v96
	v_mov_b32_e32 v3, 0
	v_lshlrev_b64 v[4:5], 2, v[0:1]
	s_lshl_b64 s[26:27], s[20:21], 2
	s_mov_b64 s[48:49], 0
	s_mov_b32 s3, 0x3fb8aa3b
	s_mov_b32 s10, 0xc2ce8ed0
	s_mov_b32 s11, 0x42b17218
	v_mov_b32_e32 v1, 0x7f800000
	s_brev_b32 s21, 18
	s_mov_b32 s35, 0xfe5163ab
	s_mov_b32 s56, 0x3c439041
	s_mov_b32 s57, 0xdb629599
	s_mov_b32 s58, 0xf534ddc0
	s_mov_b32 s59, 0xfc2757d1
	s_mov_b32 s74, 0x4e441529
	s_mov_b32 s75, 0xa2f9836e
	s_mov_b32 s76, 0x3fc90fda
	s_mov_b32 s77, 0x3f22f983
	s_mov_b32 s78, 0xbfc90fda
	v_mov_b32_e32 v16, 0x3c0881c4
	v_mov_b32_e32 v17, 0xbab64f3b
	s_brev_b32 s79, 1
	s_movk_i32 s80, 0x1f8
	s_movk_i32 s81, 0x7fff
	s_mov_b32 s82, 0xffff0000
	v_not_b32_e32 v18, 63
	v_not_b32_e32 v19, 31
	v_mov_b32_e32 v20, 0x7fc00000
	s_branch .LBB0_95
